# in-proj K-loop: per-phase s_setprio toggles removed, one static s_setprio 1 for the lagging wave group (wr=1)
# speedup vs baseline: 1.0008x; 1.0008x over previous
.LBB0_229:
	s_cmp_ge_i32 s3, s72
	s_cselect_b64 s[0:1], -1, 0
	s_cmp_lt_i32 s3, s73
	s_cselect_b64 s[4:5], -1, 0
	s_and_b64 s[0:1], s[0:1], s[4:5]
	v_writelane_b32 v255, s3, 29
	s_andn2_b64 vcc, exec, s[0:1]
	s_cbranch_vccnz .LBB0_299
	s_movk_i32 s0, 0x400
	v_mov_b32_e32 v1, v0
	v_readlane_b32 s1, v252, 8
	v_mbcnt_lo_u32_b32 v1, -1, v1
	v_mbcnt_hi_u32_b32 v1, -1, v1
	v_readlane_b32 s4, v252, 17
	s_waitcnt vmcnt(0)
	v_add_u32_e32 v8, s1, v1
	v_readlane_b32 s5, v252, 18
	s_andn2_b64 vcc, exec, s[4:5]
	v_readfirstlane_b32 s3, v8
	s_cbranch_vccnz .LBB0_248
	s_bitcmp1_b32 s3, 8
	s_cbranch_scc0 .Lprio_skip0
	s_setprio 1
.Lprio_skip0:
	v_lshlrev_b32_e32 v1, 4, v8
	v_add_u32_e32 v2, 0x2000, v1
	v_ashrrev_i32_e32 v3, 31, v2
	v_lshrrev_b32_e32 v3, 22, v3
	v_add_u32_e32 v3, v2, v3
	v_ashrrev_i32_e32 v6, 10, v3
	v_mul_i32_i24_e32 v3, 0x400, v6
	v_sub_u32_e32 v2, v2, v3
	v_lshrrev_b32_e32 v3, 4, v2
	v_bitop3_b32 v2, v3, v2, 32 bitop3:0x6c
	v_ashrrev_i32_e32 v3, 31, v2
	v_lshrrev_b32_e32 v3, 26, v3
	s_mul_i32 s36, s71, 0xc00000
	v_add_u32_e32 v3, v2, v3
	v_lshlrev_b32_e32 v4, 3, v6
	s_lshl_b64 s[4:5], s[36:37], 1
	v_readlane_b32 s1, v252, 15
	v_ashrrev_i32_e32 v7, 6, v3
	v_and_b32_e32 v4, -16, v4
	s_add_u32 s20, s1, s4
	v_readlane_b32 s1, v252, 16
	v_add_u32_e32 v4, v7, v4
	s_addc_u32 s21, s1, s5
	v_and_b32_e32 v5, 3, v7
	s_mov_b32 s5, 0x1fffe0
	v_lshrrev_b32_e32 v9, 2, v4
	v_lshlrev_b32_e32 v10, 1, v4
	v_and_b32_e32 v3, 0xc0, v3
	v_and_or_b32 v5, v4, s5, v5
	v_and_b32_e32 v9, 4, v9
	v_and_b32_e32 v10, 24, v10
	v_sub_u32_e32 v2, v2, v3
	v_mov_b32_e32 v13, 1
	v_or3_b32 v5, v5, v9, v10
	v_lshlrev_b32_e32 v9, 5, v6
	v_ashrrev_i16_sdwa v2, v13, sext(v2) dst_sel:DWORD dst_unused:UNUSED_PAD src0_sel:DWORD src1_sel:BYTE_0
	v_and_b32_e32 v10, 32, v9
	v_bfe_i32 v9, v2, 0, 16
	v_add_lshl_u32 v2, v10, v9, 1
	v_lshl_add_u32 v130, v5, 11, v2
	v_lshl_add_u32 v132, v4, 11, v2
	v_bfe_i32 v2, v8, 27, 1
	v_lshrrev_b32_e32 v2, 22, v2
	v_add_u32_e32 v2, v1, v2
	v_and_b32_e32 v2, 0xfffffc00, v2
	v_sub_u32_e32 v1, v1, v2
	v_lshrrev_b32_e32 v2, 4, v1
	v_ashrrev_i32_e32 v3, 31, v8
	v_bitop3_b32 v1, v2, v1, 32 bitop3:0x6c
	v_lshrrev_b32_e32 v3, 26, v3
	v_ashrrev_i32_e32 v2, 31, v1
	v_add_u32_e32 v3, v8, v3
	v_lshrrev_b32_e32 v2, 26, v2
	v_ashrrev_i32_e32 v11, 6, v3
	v_add_u32_e32 v2, v1, v2
	v_lshlrev_b32_e32 v3, 3, v11
	v_ashrrev_i32_e32 v10, 6, v2
	v_and_b32_e32 v3, -16, v3
	v_add_u32_e32 v3, v10, v3
	v_and_b32_e32 v4, 3, v10
	v_lshrrev_b32_e32 v5, 2, v3
	v_lshlrev_b32_e32 v12, 1, v3
	v_and_b32_e32 v2, 0xc0, v2
	s_ashr_i32 s4, s3, 6
	v_and_or_b32 v4, v3, s5, v4
	v_and_b32_e32 v5, 4, v5
	v_and_b32_e32 v12, 24, v12
	v_sub_u32_e32 v1, v1, v2
	s_ashr_i32 s1, s3, 8
	s_lshl_b32 s22, s4, 10
	v_or3_b32 v4, v4, v5, v12
	v_lshlrev_b32_e32 v5, 5, v11
	v_ashrrev_i16_sdwa v1, v13, sext(v1) dst_sel:DWORD dst_unused:UNUSED_PAD src0_sel:DWORD src1_sel:BYTE_0
	v_readlane_b32 s6, v253, 53
	v_and_b32_e32 v5, 32, v5
	v_bfe_i32 v12, v1, 0, 16
	v_readlane_b32 s7, v253, 54
	s_add_u32 s16, s20, s6
	v_add_lshl_u32 v1, v5, v12, 1
	s_addc_u32 s17, s21, s7
	s_add_i32 s23, s22, 0
	v_lshl_add_u32 v134, v4, 11, v1
	s_add_i32 m0, s23, 0x10000
	v_readlane_b32 s6, v253, 57
	global_load_lds_dwordx4 v134, s[16:17]
	s_add_i32 m0, s23, 0x12000
	v_lshl_add_u32 v136, v3, 11, v1
	global_load_lds_dwordx4 v130, s[16:17]
	s_mov_b32 m0, s23
	v_readlane_b32 s7, v253, 58
	s_add_i32 s24, s23, 0x2000
	v_mov_b32_e32 v135, v0
	v_mov_b32_e32 v131, v0
	v_lshl_add_u64 v[2:3], s[16:17], 0, v[134:135]
	v_lshl_add_u64 v[4:5], s[16:17], 0, v[130:131]
	global_load_lds_dwordx4 v136, s[6:7]
	s_mov_b32 m0, s24
	s_nop 0
	global_load_lds_dwordx4 v132, s[6:7]
	s_add_u32 s6, s16, 0x40000
	s_addc_u32 s7, s17, 0
	s_add_i32 m0, s23, 0x14000
	s_add_i32 s25, s23, 0x4000
	global_load_lds_dwordx4 v134, s[6:7]
	s_add_i32 m0, s23, 0x16000
	s_add_i32 s26, s23, 0x6000
	global_load_lds_dwordx4 v130, s[6:7]
	v_readlane_b32 s6, v253, 59
	s_mov_b32 m0, s25
	v_readlane_b32 s7, v253, 60
	s_cmp_lg_u32 s1, 1
	s_nop 3
	global_load_lds_dwordx4 v136, s[6:7]
	s_mov_b32 m0, s26
	s_nop 0
	global_load_lds_dwordx4 v132, s[6:7]
	s_cbranch_scc1 .LBB0_233
	s_barrier

.LBB0_239:
	s_add_i32 s41, s16, 2
	s_add_u32 s17, s14, 0xfffc0080
	s_addc_u32 s18, s15, -1
	s_add_i32 s42, 0, 0x10000
	v_add_u32_e32 v149, s42, v1
	ds_read_b128 v[156:159], v149
	ds_read_b128 v[160:163], v149 offset:1024
	ds_read_b128 v[164:167], v149 offset:2048
	ds_read_b128 v[168:171], v149 offset:3072
	s_cmp_eq_u32 s31, s16
	s_cselect_b32 s16, s38, s39
	s_cselect_b32 s19, s7, s18
	s_cselect_b32 s18, s9, s17
	s_cselect_b32 s17, s37, s40
	s_add_i32 m0, s23, 0xc000
	ds_read_b128 v[172:175], v151
	ds_read_b128 v[176:179], v151 offset:1024
	ds_read_b128 v[180:183], v151 offset:2048
	ds_read_b128 v[184:187], v151 offset:3072
	ds_read_b128 v[188:191], v151 offset:4096
	ds_read_b128 v[192:195], v151 offset:5120
	ds_read_b128 v[196:199], v151 offset:6144
	ds_read_b128 v[200:203], v151 offset:7168
	global_load_lds_dwordx4 v140, s[14:15]
	s_add_i32 m0, s23, 0xe000
	s_nop 0
	global_load_lds_dwordx4 v142, s[14:15]
	s_waitcnt lgkmcnt(8)
	s_barrier
	s_waitcnt lgkmcnt(0)
	s_waitcnt lgkmcnt(0)
	v_mfma_f32_16x16x32_bf16 v[122:125], v[156:159], v[172:175], v[122:125]
	v_mfma_f32_16x16x32_bf16 v[126:129], v[164:167], v[172:175], v[126:129]
	v_mfma_f32_16x16x32_bf16 v[106:109], v[156:159], v[180:183], v[106:109]
	v_mfma_f32_16x16x32_bf16 v[110:113], v[164:167], v[180:183], v[110:113]
	v_mfma_f32_16x16x32_bf16 v[90:93], v[156:159], v[188:191], v[90:93]
	v_mfma_f32_16x16x32_bf16 v[94:97], v[164:167], v[188:191], v[94:97]
	v_mfma_f32_16x16x32_bf16 v[74:77], v[156:159], v[196:199], v[74:77]
	v_mfma_f32_16x16x32_bf16 v[78:81], v[164:167], v[196:199], v[78:81]
	v_mfma_f32_16x16x32_bf16 v[122:125], v[160:163], v[176:179], v[122:125]
	v_mfma_f32_16x16x32_bf16 v[126:129], v[168:171], v[176:179], v[126:129]
	v_mfma_f32_16x16x32_bf16 v[106:109], v[160:163], v[184:187], v[106:109]
	v_mfma_f32_16x16x32_bf16 v[110:113], v[168:171], v[184:187], v[110:113]
	v_mfma_f32_16x16x32_bf16 v[90:93], v[160:163], v[192:195], v[90:93]
	v_mfma_f32_16x16x32_bf16 v[94:97], v[168:171], v[192:195], v[94:97]
	v_mfma_f32_16x16x32_bf16 v[74:77], v[160:163], v[200:203], v[74:77]
	v_mfma_f32_16x16x32_bf16 v[78:81], v[168:171], v[200:203], v[78:81]
	s_barrier
	s_add_i32 s44, 0, 0x14000
	s_add_i32 s42, s42, s22
	v_add_u32_e32 v149, s44, v1
	v_lshl_add_u64 v[230:231], s[16:17], 0, v[134:135]
	s_mov_b32 m0, s42
	ds_read_b128 v[204:207], v149
	ds_read_b128 v[208:211], v149 offset:1024
	ds_read_b128 v[212:215], v149 offset:2048
	ds_read_b128 v[226:229], v149 offset:3072
	global_load_lds_dwordx4 v[230:231], off
	v_lshl_add_u64 v[232:233], s[16:17], 0, v[130:131]
	s_add_i32 m0, s42, 0x2000
	s_nop 0
	global_load_lds_dwordx4 v[232:233], off
	s_barrier
	s_waitcnt lgkmcnt(0)
	s_waitcnt lgkmcnt(0)
	v_mfma_f32_16x16x32_bf16 v[114:117], v[204:207], v[172:175], v[114:117]
	v_mfma_f32_16x16x32_bf16 v[118:121], v[212:215], v[172:175], v[118:121]
	v_mfma_f32_16x16x32_bf16 v[98:101], v[204:207], v[180:183], v[98:101]
	v_mfma_f32_16x16x32_bf16 v[102:105], v[212:215], v[180:183], v[102:105]
	v_mfma_f32_16x16x32_bf16 v[82:85], v[204:207], v[188:191], v[82:85]
	v_mfma_f32_16x16x32_bf16 v[86:89], v[212:215], v[188:191], v[86:89]
	v_mfma_f32_16x16x32_bf16 v[66:69], v[204:207], v[196:199], v[66:69]
	v_mfma_f32_16x16x32_bf16 v[70:73], v[212:215], v[196:199], v[70:73]
	v_mfma_f32_16x16x32_bf16 v[114:117], v[208:211], v[176:179], v[114:117]
	v_mfma_f32_16x16x32_bf16 v[118:121], v[226:229], v[176:179], v[118:121]
	v_mfma_f32_16x16x32_bf16 v[98:101], v[208:211], v[184:187], v[98:101]
	v_mfma_f32_16x16x32_bf16 v[102:105], v[226:229], v[184:187], v[102:105]
	v_mfma_f32_16x16x32_bf16 v[82:85], v[208:211], v[192:195], v[82:85]
	v_mfma_f32_16x16x32_bf16 v[86:89], v[226:229], v[192:195], v[86:89]
	v_mfma_f32_16x16x32_bf16 v[66:69], v[208:211], v[200:203], v[66:69]
	v_mfma_f32_16x16x32_bf16 v[70:73], v[226:229], v[200:203], v[70:73]
	s_mov_b32 m0, s23
	v_lshl_add_u64 v[234:235], s[18:19], 0, v[136:137]
	s_barrier
	ds_read_b128 v[172:175], v151 offset:16384
	ds_read_b128 v[176:179], v151 offset:17408
	ds_read_b128 v[180:183], v151 offset:18432
	ds_read_b128 v[184:187], v151 offset:19456
	ds_read_b128 v[188:191], v151 offset:20480
	ds_read_b128 v[192:195], v151 offset:21504
	ds_read_b128 v[196:199], v151 offset:22528
	ds_read_b128 v[200:203], v151 offset:23552
	global_load_lds_dwordx4 v[234:235], off
	v_lshl_add_u64 v[236:237], s[18:19], 0, v[132:133]
	s_mov_b32 m0, s24
	s_nop 0
	global_load_lds_dwordx4 v[236:237], off
	s_barrier
	s_waitcnt lgkmcnt(0)
	s_waitcnt lgkmcnt(0)
	v_mfma_f32_16x16x32_bf16 v[58:61], v[156:159], v[172:175], v[58:61]
	v_mfma_f32_16x16x32_bf16 v[62:65], v[164:167], v[172:175], v[62:65]
	v_mfma_f32_16x16x32_bf16 v[42:45], v[156:159], v[180:183], v[42:45]
	v_mfma_f32_16x16x32_bf16 v[46:49], v[164:167], v[180:183], v[46:49]
	v_mfma_f32_16x16x32_bf16 v[26:29], v[156:159], v[188:191], v[26:29]
	v_mfma_f32_16x16x32_bf16 v[30:33], v[164:167], v[188:191], v[30:33]
	v_mfma_f32_16x16x32_bf16 v[10:13], v[156:159], v[196:199], v[10:13]
	v_mfma_f32_16x16x32_bf16 v[14:17], v[164:167], v[196:199], v[14:17]
	v_mfma_f32_16x16x32_bf16 v[58:61], v[160:163], v[176:179], v[58:61]
	v_mfma_f32_16x16x32_bf16 v[62:65], v[168:171], v[176:179], v[62:65]
	v_mfma_f32_16x16x32_bf16 v[42:45], v[160:163], v[184:187], v[42:45]
	v_mfma_f32_16x16x32_bf16 v[46:49], v[168:171], v[184:187], v[46:49]
	v_mfma_f32_16x16x32_bf16 v[26:29], v[160:163], v[192:195], v[26:29]
	v_mfma_f32_16x16x32_bf16 v[30:33], v[168:171], v[192:195], v[30:33]
	v_mfma_f32_16x16x32_bf16 v[10:13], v[160:163], v[200:203], v[10:13]
	v_mfma_f32_16x16x32_bf16 v[14:17], v[168:171], v[200:203], v[14:17]
	s_barrier
	s_add_u32 s42, s16, 0x40000
	s_addc_u32 s43, s17, 0
	s_add_i32 s44, s44, s22
	s_mov_b32 m0, s44
	s_nop 0
	global_load_lds_dwordx4 v134, s[42:43]
	s_add_i32 m0, s44, 0x2000
	s_nop 0
	global_load_lds_dwordx4 v130, s[42:43]
	s_cmp_eq_u32 s100, 0
	s_cbranch_scc1 .Lip_w4n
	s_waitcnt vmcnt(24)
	s_branch .Lip_w4d

.Lip_w4d:
	s_barrier
	v_mfma_f32_16x16x32_bf16 v[50:53], v[204:207], v[172:175], v[50:53]
	v_mfma_f32_16x16x32_bf16 v[54:57], v[212:215], v[172:175], v[54:57]
	v_mfma_f32_16x16x32_bf16 v[34:37], v[204:207], v[180:183], v[34:37]
	v_mfma_f32_16x16x32_bf16 v[38:41], v[212:215], v[180:183], v[38:41]
	v_mfma_f32_16x16x32_bf16 v[18:21], v[204:207], v[188:191], v[18:21]
	v_mfma_f32_16x16x32_bf16 v[22:25], v[212:215], v[188:191], v[22:25]
	v_mfma_f32_16x16x32_bf16 v[6:9], v[204:207], v[196:199], v[6:9]
	v_mfma_f32_16x16x32_bf16 v[2:5], v[212:215], v[196:199], v[2:5]
	v_mfma_f32_16x16x32_bf16 v[50:53], v[208:211], v[176:179], v[50:53]
	v_mfma_f32_16x16x32_bf16 v[54:57], v[226:229], v[176:179], v[54:57]
	v_mfma_f32_16x16x32_bf16 v[34:37], v[208:211], v[184:187], v[34:37]
	v_mfma_f32_16x16x32_bf16 v[38:41], v[226:229], v[184:187], v[38:41]
	v_mfma_f32_16x16x32_bf16 v[18:21], v[208:211], v[192:195], v[18:21]
	v_mfma_f32_16x16x32_bf16 v[22:25], v[226:229], v[192:195], v[22:25]
	v_mfma_f32_16x16x32_bf16 v[6:9], v[208:211], v[200:203], v[6:9]
	v_mfma_f32_16x16x32_bf16 v[2:5], v[226:229], v[200:203], v[2:5]
	s_add_i32 s42, 0, 0x18000
	v_add_u32_e32 v149, s42, v1
	s_barrier
	ds_read_b128 v[156:159], v149
	ds_read_b128 v[160:163], v149 offset:1024
	ds_read_b128 v[164:167], v149 offset:2048
	ds_read_b128 v[168:171], v149 offset:3072
	s_add_u32 s18, s18, 0x40000
	s_addc_u32 s19, s19, 0
	s_mov_b32 m0, s25
	ds_read_b128 v[172:175], v151 offset:32768
	ds_read_b128 v[176:179], v151 offset:33792
	ds_read_b128 v[180:183], v151 offset:34816
	ds_read_b128 v[184:187], v151 offset:35840
	ds_read_b128 v[188:191], v151 offset:36864
	ds_read_b128 v[192:195], v151 offset:37888
	ds_read_b128 v[196:199], v151 offset:38912
	ds_read_b128 v[200:203], v151 offset:39936
	global_load_lds_dwordx4 v136, s[18:19]
	s_mov_b32 m0, s26
	s_nop 0
	global_load_lds_dwordx4 v132, s[18:19]
	s_waitcnt lgkmcnt(8)
	s_barrier
	s_waitcnt lgkmcnt(0)
	s_waitcnt lgkmcnt(0)
	v_mfma_f32_16x16x32_bf16 v[122:125], v[156:159], v[172:175], v[122:125]
	v_mfma_f32_16x16x32_bf16 v[126:129], v[164:167], v[172:175], v[126:129]
	v_mfma_f32_16x16x32_bf16 v[106:109], v[156:159], v[180:183], v[106:109]
	v_mfma_f32_16x16x32_bf16 v[110:113], v[164:167], v[180:183], v[110:113]
	v_mfma_f32_16x16x32_bf16 v[90:93], v[156:159], v[188:191], v[90:93]
	v_mfma_f32_16x16x32_bf16 v[94:97], v[164:167], v[188:191], v[94:97]
	v_mfma_f32_16x16x32_bf16 v[74:77], v[156:159], v[196:199], v[74:77]
	v_mfma_f32_16x16x32_bf16 v[78:81], v[164:167], v[196:199], v[78:81]
	v_mfma_f32_16x16x32_bf16 v[122:125], v[160:163], v[176:179], v[122:125]
	v_mfma_f32_16x16x32_bf16 v[126:129], v[168:171], v[176:179], v[126:129]
	v_mfma_f32_16x16x32_bf16 v[106:109], v[160:163], v[184:187], v[106:109]
	v_mfma_f32_16x16x32_bf16 v[110:113], v[168:171], v[184:187], v[110:113]
	v_mfma_f32_16x16x32_bf16 v[90:93], v[160:163], v[192:195], v[90:93]
	v_mfma_f32_16x16x32_bf16 v[94:97], v[168:171], v[192:195], v[94:97]
	v_mfma_f32_16x16x32_bf16 v[74:77], v[160:163], v[200:203], v[74:77]
	v_mfma_f32_16x16x32_bf16 v[78:81], v[168:171], v[200:203], v[78:81]
	s_barrier
	s_add_i32 s18, 0, 0x1c000
	s_add_i32 s19, s42, s22
	v_add_u32_e32 v149, s18, v1
	v_lshl_add_u64 v[230:231], v[230:231], 0, s[74:75]
	s_mov_b32 m0, s19
	ds_read_b128 v[204:207], v149
	ds_read_b128 v[208:211], v149 offset:1024
	ds_read_b128 v[212:215], v149 offset:2048
	ds_read_b128 v[226:229], v149 offset:3072
	global_load_lds_dwordx4 v[230:231], off
	v_lshl_add_u64 v[230:231], v[232:233], 0, s[74:75]
	s_add_i32 m0, s19, 0x2000
	s_nop 0
	global_load_lds_dwordx4 v[230:231], off
	s_cmp_eq_u32 s100, 0
	s_cbranch_scc1 .Lip_w6n
	s_waitcnt vmcnt(10)
	s_mov_b32 s100, 0
.Lip_w6n:
	s_barrier
	s_waitcnt lgkmcnt(0)
	s_waitcnt lgkmcnt(0)
	v_mfma_f32_16x16x32_bf16 v[114:117], v[204:207], v[172:175], v[114:117]
	v_mfma_f32_16x16x32_bf16 v[118:121], v[212:215], v[172:175], v[118:121]
	v_mfma_f32_16x16x32_bf16 v[98:101], v[204:207], v[180:183], v[98:101]
	v_mfma_f32_16x16x32_bf16 v[102:105], v[212:215], v[180:183], v[102:105]
	v_mfma_f32_16x16x32_bf16 v[82:85], v[204:207], v[188:191], v[82:85]
	v_mfma_f32_16x16x32_bf16 v[86:89], v[212:215], v[188:191], v[86:89]
	v_mfma_f32_16x16x32_bf16 v[66:69], v[204:207], v[196:199], v[66:69]
	v_mfma_f32_16x16x32_bf16 v[70:73], v[212:215], v[196:199], v[70:73]
	v_mfma_f32_16x16x32_bf16 v[114:117], v[208:211], v[176:179], v[114:117]
	v_mfma_f32_16x16x32_bf16 v[118:121], v[226:229], v[176:179], v[118:121]
	v_mfma_f32_16x16x32_bf16 v[98:101], v[208:211], v[184:187], v[98:101]
	v_mfma_f32_16x16x32_bf16 v[102:105], v[226:229], v[184:187], v[102:105]
	v_mfma_f32_16x16x32_bf16 v[82:85], v[208:211], v[192:195], v[82:85]
	v_mfma_f32_16x16x32_bf16 v[86:89], v[226:229], v[192:195], v[86:89]
	v_mfma_f32_16x16x32_bf16 v[66:69], v[208:211], v[200:203], v[66:69]
	v_mfma_f32_16x16x32_bf16 v[70:73], v[226:229], v[200:203], v[70:73]
	s_mov_b32 m0, s28
	v_lshl_add_u64 v[230:231], v[234:235], 0, s[74:75]
	s_barrier
	ds_read_b128 v[172:175], v151 offset:49152
	ds_read_b128 v[176:179], v151 offset:50176
	ds_read_b128 v[180:183], v151 offset:51200
	ds_read_b128 v[184:187], v151 offset:52224
	ds_read_b128 v[188:191], v151 offset:53248
	ds_read_b128 v[192:195], v151 offset:54272
	ds_read_b128 v[196:199], v151 offset:55296
	ds_read_b128 v[200:203], v151 offset:56320
	global_load_lds_dwordx4 v[230:231], off
	v_lshl_add_u64 v[230:231], v[236:237], 0, s[74:75]
	s_mov_b32 m0, s29
	s_nop 0
	global_load_lds_dwordx4 v[230:231], off
	s_barrier
	s_waitcnt lgkmcnt(0)
	s_waitcnt lgkmcnt(0)
	v_mfma_f32_16x16x32_bf16 v[58:61], v[156:159], v[172:175], v[58:61]
	v_mfma_f32_16x16x32_bf16 v[62:65], v[164:167], v[172:175], v[62:65]
	v_mfma_f32_16x16x32_bf16 v[42:45], v[156:159], v[180:183], v[42:45]
	v_mfma_f32_16x16x32_bf16 v[46:49], v[164:167], v[180:183], v[46:49]
	v_mfma_f32_16x16x32_bf16 v[26:29], v[156:159], v[188:191], v[26:29]
	v_mfma_f32_16x16x32_bf16 v[30:33], v[164:167], v[188:191], v[30:33]
	v_mfma_f32_16x16x32_bf16 v[10:13], v[156:159], v[196:199], v[10:13]
	v_mfma_f32_16x16x32_bf16 v[14:17], v[164:167], v[196:199], v[14:17]
	v_mfma_f32_16x16x32_bf16 v[58:61], v[160:163], v[176:179], v[58:61]
	v_mfma_f32_16x16x32_bf16 v[62:65], v[168:171], v[176:179], v[62:65]
	v_mfma_f32_16x16x32_bf16 v[42:45], v[160:163], v[184:187], v[42:45]
	v_mfma_f32_16x16x32_bf16 v[46:49], v[168:171], v[184:187], v[46:49]
	v_mfma_f32_16x16x32_bf16 v[26:29], v[160:163], v[192:195], v[26:29]
	v_mfma_f32_16x16x32_bf16 v[30:33], v[168:171], v[192:195], v[30:33]
	v_mfma_f32_16x16x32_bf16 v[10:13], v[160:163], v[200:203], v[10:13]
	v_mfma_f32_16x16x32_bf16 v[14:17], v[168:171], v[200:203], v[14:17]
	s_barrier
	s_add_u32 s16, s16, 0x40080
	s_addc_u32 s17, s17, 0
	s_add_i32 s18, s18, s22
	s_mov_b32 m0, s18
	s_nop 0
	global_load_lds_dwordx4 v134, s[16:17]
	s_add_i32 m0, s18, 0x2000
	s_nop 0
	global_load_lds_dwordx4 v130, s[16:17]
	s_waitcnt vmcnt(6)
	s_barrier
	v_mfma_f32_16x16x32_bf16 v[50:53], v[204:207], v[172:175], v[50:53]
	v_mfma_f32_16x16x32_bf16 v[54:57], v[212:215], v[172:175], v[54:57]
	v_mfma_f32_16x16x32_bf16 v[34:37], v[204:207], v[180:183], v[34:37]
	v_mfma_f32_16x16x32_bf16 v[38:41], v[212:215], v[180:183], v[38:41]
	v_mfma_f32_16x16x32_bf16 v[18:21], v[204:207], v[188:191], v[18:21]
	v_mfma_f32_16x16x32_bf16 v[22:25], v[212:215], v[188:191], v[22:25]
	v_mfma_f32_16x16x32_bf16 v[6:9], v[204:207], v[196:199], v[6:9]
	v_mfma_f32_16x16x32_bf16 v[2:5], v[212:215], v[196:199], v[2:5]
	v_mfma_f32_16x16x32_bf16 v[50:53], v[208:211], v[176:179], v[50:53]
	v_mfma_f32_16x16x32_bf16 v[54:57], v[226:229], v[176:179], v[54:57]
	v_mfma_f32_16x16x32_bf16 v[34:37], v[208:211], v[184:187], v[34:37]
	v_mfma_f32_16x16x32_bf16 v[38:41], v[226:229], v[184:187], v[38:41]
	v_mfma_f32_16x16x32_bf16 v[18:21], v[208:211], v[192:195], v[18:21]
	v_mfma_f32_16x16x32_bf16 v[22:25], v[226:229], v[192:195], v[22:25]
	v_mfma_f32_16x16x32_bf16 v[6:9], v[208:211], v[200:203], v[6:9]
	v_mfma_f32_16x16x32_bf16 v[2:5], v[226:229], v[200:203], v[2:5]
	s_add_u32 s14, s14, 0x100
	s_addc_u32 s15, s15, 0
	s_add_u32 s39, s39, 0x100
	s_addc_u32 s40, s40, 0
	s_cmp_ge_i32 s41, s27
	s_mov_b32 s16, s41
	s_barrier
	s_cbranch_scc0 .LBB0_239
	v_readlane_b32 s38, v255, 8
	v_mov_b32_e32 v203, v155
	v_readlane_b32 s39, v255, 9
	s_cmp_lt_i32 s35, 32
	s_mov_b64 s[14:15], -1
	s_cbranch_scc1 .LBB0_243

.LBB0_245:
	s_setprio 0
	s_waitcnt vmcnt(0)
	s_cmpk_gt_u32 s3, 0xff
	v_readlane_b32 s35, v255, 10
	s_cbranch_scc1 .LBB0_247
	s_barrier
